# attention loop: K-fragment LDS reads reordered so the first k-half of all four key blocks arrives first, waits re-counted (7/4/2/0)
# speedup vs baseline: 1.0033x; 1.0033x over previous
; template <bool SAMPLE> __device__ __forceinline__ void attn_unit16(const Ctx& c, LAS unsigned char* lds, int b, int h, int qb, int wave_s) {
;     ...
;         if (!SAMPLE) {
;             const int kidx0 = j == 0 ? 0 : 16 + 64 * (j - 1);
;             const size_t rr = (size_t)(b * 8 + h) * KROWS + kidx0 + lrow;
;             const bf16* p = (const bf16*)(ws + (isk ? WS_DK : WS_DV)) + rr * 128;
;             r0 = *(const u32x4*)(p + lck * 8); r1 = *(const u32x4*)(p + 64 + lck * 8);
.Lq1_body:
	global_load_dwordx4 v[28:31], v202, s[100:101] offset:-128
	global_load_dwordx4 v[32:35], v202, s[100:101]
	global_load_dwordx4 v[4:7], v203, s[100:101] offset:-128
	global_load_dwordx4 v[12:15], v203, s[100:101]
	ds_read_b128 v[44:47], v214 offset:35840
	ds_read_b128 v[92:95], v214 offset:40192
	ds_read_b128 v[132:135], v214 offset:44544
	ds_read_b128 v[136:139], v214 offset:48896
	ds_read_b128 v[72:75], v214 offset:35904
	ds_read_b128 v[112:115], v214 offset:40256
	ds_read_b128 v[148:151], v214 offset:44608
	ds_read_b128 v[152:155], v214 offset:48960
	s_waitcnt lgkmcnt(7)
	v_mfma_f32_16x16x32_bf16 v[140:143], v[44:47], v[8:11], 0
	v_mfma_f32_16x16x32_bf16 v[44:47], v[44:47], v[20:23], 0
	s_waitcnt lgkmcnt(4)
	v_mfma_f32_16x16x32_bf16 v[156:159], v[92:95], v[8:11], 0
	v_mfma_f32_16x16x32_bf16 v[92:95], v[92:95], v[20:23], 0
	v_mfma_f32_16x16x32_bf16 v[160:163], v[132:135], v[8:11], 0
	v_mfma_f32_16x16x32_bf16 v[132:135], v[132:135], v[20:23], 0
	v_mfma_f32_16x16x32_bf16 v[164:167], v[136:139], v[8:11], 0
	v_mfma_f32_16x16x32_bf16 v[168:171], v[136:139], v[20:23], 0
	s_waitcnt lgkmcnt(2)
	v_mfma_f32_16x16x32_bf16 v[144:147], v[72:75], v[16:19], v[140:143]
	v_mfma_f32_16x16x32_bf16 v[136:139], v[72:75], v[24:27], v[44:47]
	v_mfma_f32_16x16x32_bf16 v[44:47], v[112:115], v[16:19], v[156:159]
	v_mfma_f32_16x16x32_bf16 v[92:95], v[112:115], v[24:27], v[92:95]
	s_waitcnt lgkmcnt(0)
	v_mfma_f32_16x16x32_bf16 v[140:143], v[148:151], v[16:19], v[160:163]
	v_mfma_f32_16x16x32_bf16 v[132:135], v[148:151], v[24:27], v[132:135]
	v_mfma_f32_16x16x32_bf16 v[72:75], v[152:155], v[16:19], v[164:167]
	v_mfma_f32_16x16x32_bf16 v[112:115], v[152:155], v[24:27], v[168:171]
	s_cmp_eq_u32 s98, 0
	s_cbranch_scc1 .LBB0_859
	v_sub_f32_e32 v147, v147, v196
	v_sub_f32_e32 v146, v146, v196
	v_sub_f32_e32 v145, v145, v196
	v_sub_f32_e32 v144, v144, v196
	v_sub_f32_e32 v47, v47, v196
	v_sub_f32_e32 v46, v46, v196
	v_sub_f32_e32 v45, v45, v196
	v_sub_f32_e32 v44, v44, v196
	v_sub_f32_e32 v143, v143, v196
	v_sub_f32_e32 v142, v142, v196
	v_sub_f32_e32 v141, v141, v196
	v_sub_f32_e32 v140, v140, v196
	v_sub_f32_e32 v75, v75, v196
	v_sub_f32_e32 v74, v74, v196
	v_sub_f32_e32 v73, v73, v196
	v_sub_f32_e32 v72, v72, v196
	v_sub_f32_e32 v139, v139, v197
	v_sub_f32_e32 v138, v138, v197
	v_sub_f32_e32 v137, v137, v197
	v_sub_f32_e32 v136, v136, v197
	v_sub_f32_e32 v95, v95, v197
	v_sub_f32_e32 v94, v94, v197
	v_sub_f32_e32 v93, v93, v197
	v_sub_f32_e32 v92, v92, v197
	v_sub_f32_e32 v135, v135, v197
	v_sub_f32_e32 v134, v134, v197
	v_sub_f32_e32 v133, v133, v197
	v_sub_f32_e32 v132, v132, v197
	v_sub_f32_e32 v115, v115, v197
	v_sub_f32_e32 v114, v114, v197
	v_sub_f32_e32 v113, v113, v197
	v_sub_f32_e32 v112, v112, v197

; template <bool SAMPLE> __device__ __forceinline__ void attn_unit16(const Ctx& c, LAS unsigned char* lds, int b, int h, int qb, int wave_s) {
;     ...
;         if (!SAMPLE) {
;             const int kidx0 = j == 0 ? 0 : 16 + 64 * (j - 1);
;             const size_t rr = (size_t)(b * 8 + h) * KROWS + kidx0 + lrow;
;             const bf16* p = (const bf16*)(ws + (isk ? WS_DK : WS_DV)) + rr * 128;
;             r0 = *(const u32x4*)(p + lck * 8); r1 = *(const u32x4*)(p + 64 + lck * 8);
.Lq1_h2_nok:
	global_load_dwordx4 v[4:7], v203, s[100:101] offset:-128
	global_load_dwordx4 v[12:15], v203, s[100:101]
	s_cmp_ge_u32 s89, s83
	s_cbranch_scc1 .Lq1_h2_pvonly
	ds_read_b128 v[36:39], v214
	ds_read_b128 v[60:63], v214 offset:4352
	ds_read_b128 v[64:67], v214 offset:8704
	ds_read_b128 v[108:111], v214 offset:13056
	ds_read_b128 v[40:43], v214 offset:64
	ds_read_b128 v[84:87], v214 offset:4416
	ds_read_b128 v[124:127], v214 offset:8768
	ds_read_b128 v[100:103], v214 offset:13120
	s_waitcnt lgkmcnt(7)
	v_mfma_f32_16x16x32_bf16 v[120:123], v[36:39], v[8:11], 0
	v_mfma_f32_16x16x32_bf16 v[36:39], v[36:39], v[20:23], 0
	s_waitcnt lgkmcnt(4)
	v_mfma_f32_16x16x32_bf16 v[116:119], v[60:63], v[8:11], 0
	v_mfma_f32_16x16x32_bf16 v[60:63], v[60:63], v[20:23], 0
	v_mfma_f32_16x16x32_bf16 v[96:99], v[64:67], v[8:11], 0
	v_mfma_f32_16x16x32_bf16 v[64:67], v[64:67], v[20:23], 0
	v_mfma_f32_16x16x32_bf16 v[104:107], v[108:111], v[8:11], 0
	v_mfma_f32_16x16x32_bf16 v[76:79], v[108:111], v[20:23], 0
	s_waitcnt lgkmcnt(2)
	v_mfma_f32_16x16x32_bf16 v[128:131], v[40:43], v[16:19], v[120:123]
	v_mfma_f32_16x16x32_bf16 v[108:111], v[40:43], v[24:27], v[36:39]
	v_mfma_f32_16x16x32_bf16 v[36:39], v[84:87], v[16:19], v[116:119]
	v_mfma_f32_16x16x32_bf16 v[60:63], v[84:87], v[24:27], v[60:63]
	s_waitcnt lgkmcnt(0)
	v_mfma_f32_16x16x32_bf16 v[120:123], v[124:127], v[16:19], v[96:99]
	v_mfma_f32_16x16x32_bf16 v[64:67], v[124:127], v[24:27], v[64:67]
	v_mfma_f32_16x16x32_bf16 v[40:43], v[100:103], v[16:19], v[104:107]
	v_mfma_f32_16x16x32_bf16 v[84:87], v[100:103], v[24:27], v[76:79]
	s_cmp_eq_u32 s98, 0
	s_cbranch_scc1 .LBB0_875
	v_sub_f32_e32 v131, v131, v196
	v_sub_f32_e32 v130, v130, v196
	v_sub_f32_e32 v129, v129, v196
	v_sub_f32_e32 v128, v128, v196
	v_sub_f32_e32 v39, v39, v196
	v_sub_f32_e32 v38, v38, v196
	v_sub_f32_e32 v37, v37, v196
	v_sub_f32_e32 v36, v36, v196
	v_sub_f32_e32 v123, v123, v196
	v_sub_f32_e32 v122, v122, v196
	v_sub_f32_e32 v121, v121, v196
	v_sub_f32_e32 v120, v120, v196
	v_sub_f32_e32 v43, v43, v196
	v_sub_f32_e32 v42, v42, v196
	v_sub_f32_e32 v41, v41, v196
	v_sub_f32_e32 v40, v40, v196
	v_sub_f32_e32 v111, v111, v197
	v_sub_f32_e32 v110, v110, v197
	v_sub_f32_e32 v109, v109, v197
	v_sub_f32_e32 v108, v108, v197
	v_sub_f32_e32 v63, v63, v197
	v_sub_f32_e32 v62, v62, v197
	v_sub_f32_e32 v61, v61, v197
	v_sub_f32_e32 v60, v60, v197
	v_sub_f32_e32 v67, v67, v197
	v_sub_f32_e32 v66, v66, v197
	v_sub_f32_e32 v65, v65, v197
	v_sub_f32_e32 v64, v64, v197
	v_sub_f32_e32 v87, v87, v197
	v_sub_f32_e32 v86, v86, v197
	v_sub_f32_e32 v85, v85, v197
	v_sub_f32_e32 v84, v84, v197
